# attention tile loop: K/V staging loads use 32-bit lane offsets with one scalar base (saddr form), 5 VALU instead of 11 per tile
# speedup vs baseline: 1.0072x; 1.0021x over previous
.LBB0_520:
	v_mov_b32_e32 v218, v3
	s_and_b32 s56, s60, 0xffffff80
	s_sub_i32 s79, s66, s56
	s_lshl_b32 s4, s60, 8
	v_add_u32_e32 v184, s79, v198
	s_and_b32 s8, s4, 0x7800
	v_ashrrev_i32_e32 v185, 31, v184
	v_lshl_add_u64 v[182:183], v[184:185], 0, s[8:9]
	s_and_b32 s78, s60, 7
	v_lshlrev_b64 v[4:5], 11, v[182:183]
	v_lshl_add_u64 v[4:5], s[38:39], 0, v[4:5]
	s_lshl_b32 s4, s78, 8
	s_mov_b32 s5, s9
	v_lshl_add_u64 v[4:5], v[4:5], 0, s[4:5]
	v_lshl_add_u64 v[4:5], v[4:5], 0, s[14:15]
	v_mov_b32_e32 v179, v3
	v_lshl_add_u64 v[4:5], v[4:5], 0, v[178:179]
	global_load_dwordx4 v[114:117], v[4:5], off
	global_load_dwordx4 v[118:121], v[4:5], off offset:32
	global_load_dwordx4 v[122:125], v[4:5], off offset:64
	global_load_dwordx4 v[126:129], v[4:5], off offset:96
	s_add_i32 s5, s78, 1
	s_ashr_i32 s57, s60, 6
	v_cvt_f32_ubyte0_e32 v18, s5
	s_and_b32 s58, s57, -2
	v_cmp_lt_f32_e32 vcc, s72, v18
	s_and_b64 s[60:61], vcc, exec
	s_cselect_b32 s59, 0xffffffc0, 0
	s_lshl_b32 s5, s8, 11
	s_add_u32 s8, s63, s5
	s_addc_u32 s61, s64, 0
	s_add_u32 s60, s8, s4
	s_addc_u32 s61, s61, 0
	s_mov_b64 s[100:101], s[60:61]
	s_add_u32 s5, s65, s5
	s_addc_u32 s8, s70, 0
	s_add_u32 s4, s5, s4
	s_addc_u32 s5, s8, 0
	s_sub_i32 s8, 31, s58
	v_mov_b32_e32 v181, v3
	v_lshl_or_b32 v2, s8, 6, v199
	v_lshl_add_u64 v[186:187], s[60:61], 0, v[180:181]
	v_lshlrev_b64 v[6:7], 11, v[2:3]
	s_lshl_b32 s60, s58, 6
	v_lshl_add_u64 v[8:9], v[186:187], 0, v[6:7]
	v_cndmask_b32_e32 v19, 0, v215, vcc
	v_lshl_add_u64 v[188:189], s[4:5], 0, v[180:181]
	v_subrev_u32_e32 v4, s60, v199
	v_add_co_u32_e32 v12, vcc, s73, v8
	v_add_u32_e32 v2, 0x780, v4
	v_lshl_add_u64 v[6:7], v[188:189], 0, v[6:7]
	v_addc_co_u32_e32 v13, vcc, 0, v9, vcc
	v_lshlrev_b64 v[10:11], 11, v[2:3]
	v_add_co_u32_e32 v14, vcc, s73, v6
	v_lshl_add_u64 v[16:17], v[186:187], 0, v[10:11]
	s_nop 0
	v_addc_co_u32_e32 v15, vcc, 0, v7, vcc
	global_load_dwordx4 v[134:137], v[8:9], off
	global_load_dwordx4 v[154:157], v[12:13], off
	global_load_dwordx4 v[146:149], v[6:7], off
	global_load_dwordx4 v[158:161], v[14:15], off
	v_add_co_u32_e32 v6, vcc, s73, v16
	v_lshl_add_u64 v[10:11], v[188:189], 0, v[10:11]
	s_nop 0
	v_addc_co_u32_e32 v7, vcc, 0, v17, vcc
	v_add_co_u32_e32 v8, vcc, s73, v10
	s_waitcnt vmcnt(7)
	v_and_b32_e32 v5, 0xffff0000, v114
	v_lshlrev_b32_e32 v2, 16, v114
	v_mul_f32_e32 v5, v5, v5
	v_addc_co_u32_e32 v9, vcc, 0, v11, vcc
	global_load_dwordx4 v[130:133], v[16:17], off
	global_load_dwordx4 v[142:145], v[6:7], off
	global_load_dwordx4 v[138:141], v[10:11], off
	global_load_dwordx4 v[150:153], v[8:9], off
	v_lshlrev_b32_e32 v6, 16, v115
	v_fmac_f32_e32 v5, v2, v2
	v_and_b32_e32 v7, 0xffff0000, v115
	v_fmac_f32_e32 v5, v6, v6
	v_lshlrev_b32_e32 v8, 16, v116
	v_fmac_f32_e32 v5, v7, v7
	v_and_b32_e32 v9, 0xffff0000, v116
	v_fmac_f32_e32 v5, v8, v8
	v_lshlrev_b32_e32 v10, 16, v117
	v_fmac_f32_e32 v5, v9, v9
	v_and_b32_e32 v11, 0xffff0000, v117
	v_fmac_f32_e32 v5, v10, v10
	s_waitcnt vmcnt(10)
	v_lshlrev_b32_e32 v12, 16, v118
	v_fmac_f32_e32 v5, v11, v11
	v_and_b32_e32 v13, 0xffff0000, v118
	v_fmac_f32_e32 v5, v12, v12
	v_lshlrev_b32_e32 v14, 16, v119
	v_fmac_f32_e32 v5, v13, v13
	v_and_b32_e32 v15, 0xffff0000, v119
	v_fmac_f32_e32 v5, v14, v14
	v_lshlrev_b32_e32 v16, 16, v120
	v_fmac_f32_e32 v5, v15, v15
	v_and_b32_e32 v17, 0xffff0000, v120
	v_fmac_f32_e32 v5, v16, v16
	v_lshlrev_b32_e32 v20, 16, v121
	v_fmac_f32_e32 v5, v17, v17
	v_and_b32_e32 v21, 0xffff0000, v121
	v_fmac_f32_e32 v5, v20, v20
	v_fmac_f32_e32 v5, v21, v21
	s_waitcnt vmcnt(9)
	v_lshlrev_b32_e32 v2, 16, v122
	v_fmac_f32_e32 v5, v2, v2
	v_and_b32_e32 v2, 0xffff0000, v122
	v_fmac_f32_e32 v5, v2, v2
	v_lshlrev_b32_e32 v2, 16, v123
	v_fmac_f32_e32 v5, v2, v2
	v_and_b32_e32 v2, 0xffff0000, v123
	v_fmac_f32_e32 v5, v2, v2
	v_lshlrev_b32_e32 v2, 16, v124
	v_fmac_f32_e32 v5, v2, v2
	v_and_b32_e32 v2, 0xffff0000, v124
	v_fmac_f32_e32 v5, v2, v2
	v_lshlrev_b32_e32 v2, 16, v125
	v_fmac_f32_e32 v5, v2, v2
	v_and_b32_e32 v2, 0xffff0000, v125
	v_fmac_f32_e32 v5, v2, v2
	s_waitcnt vmcnt(8)
	v_lshlrev_b32_e32 v2, 16, v126
	v_fmac_f32_e32 v5, v2, v2
	v_and_b32_e32 v2, 0xffff0000, v126
	v_fmac_f32_e32 v5, v2, v2
	v_lshlrev_b32_e32 v2, 16, v127
	v_fmac_f32_e32 v5, v2, v2
	v_and_b32_e32 v2, 0xffff0000, v127
	v_fmac_f32_e32 v5, v2, v2
	v_lshlrev_b32_e32 v2, 16, v128
	v_fmac_f32_e32 v5, v2, v2
	v_and_b32_e32 v2, 0xffff0000, v128
	v_fmac_f32_e32 v5, v2, v2
	v_lshlrev_b32_e32 v2, 16, v129
	v_fmac_f32_e32 v5, v2, v2
	v_and_b32_e32 v2, 0xffff0000, v129
	v_fmac_f32_e32 v5, v2, v2
	ds_bpermute_b32 v2, v197, v5
	v_sub_f32_e32 v6, v19, v18
	v_exp_f32_e32 v6, v6
	s_waitcnt lgkmcnt(0)
	v_add_f32_e32 v2, v5, v2
	v_mul_f32_e32 v5, 0x4f800000, v2
	v_cmp_gt_f32_e32 vcc, s71, v2
	v_ldexp_f32 v6, v6, s59
	v_mul_f32_e32 v190, 0x3fb8aa3b, v6
	v_cndmask_b32_e32 v2, v2, v5, vcc
	v_sqrt_f32_e32 v5, v2
	s_nop 0
	v_add_u32_e32 v6, -1, v5
	v_fma_f32 v7, -v6, v5, v2
	v_cmp_ge_f32_e64 s[4:5], 0, v7
	v_add_u32_e32 v7, 1, v5
	s_nop 0
	v_cndmask_b32_e64 v6, v5, v6, s[4:5]
	v_fma_f32 v5, -v7, v5, v2
	v_cmp_lt_f32_e64 s[4:5], 0, v5
	s_nop 1
	v_cndmask_b32_e64 v5, v6, v7, s[4:5]
	v_mul_f32_e32 v6, 0x37800000, v5
	v_cndmask_b32_e32 v5, v5, v6, vcc
	v_cmp_class_f32_e32 vcc, v2, v200
	s_nop 1
	v_cndmask_b32_e32 v2, v5, v2, vcc
	v_mul_f32_e32 v5, v201, v2
	v_fmaak_f32 v2, 2.0, v5, 0x42200000
	v_div_scale_f32 v6, s[4:5], v190, v190, v2
	v_rcp_f32_e32 v7, v6
	s_nop 0
	v_fma_f32 v8, -v6, v7, 1.0
	v_fmac_f32_e32 v7, v8, v7
	v_div_scale_f32 v8, vcc, v2, v190, v2
	v_mul_f32_e32 v9, v8, v7
	v_fma_f32 v10, -v6, v9, v8
	v_fmac_f32_e32 v9, v10, v7
	v_fma_f32 v6, -v6, v9, v8
	v_div_fmas_f32 v6, v6, v7, v9
	v_div_fixup_f32 v2, v6, v190, v2
	s_nop 1
	v_max_f32_dpp v2, v2, v2 quad_perm:[1,0,3,2] row_mask:0xf bank_mask:0xf
	s_nop 1
	v_max_f32_dpp v2, v2, v2 quad_perm:[2,3,0,1] row_mask:0xf bank_mask:0xf
	s_nop 1
	v_max_f32_dpp v2, v2, v2 row_half_mirror row_mask:0xf bank_mask:0xf
	s_nop 1
	v_max_f32_dpp v2, v2, v2 row_mirror row_mask:0xf bank_mask:0xf
	s_nop 1
	v_max_f32_dpp v2, v2, v2 row_bcast:15 row_mask:0xa bank_mask:0xf
	s_nop 1
	v_readlane_b32 s98, v2, 31
	s_and_saveexec_b64 s[4:5], s[0:1]
	s_cbranch_execz .LBB0_526
	s_nop 0
	v_mov_b32_e32 v2, s98
	v_mov_b32_e32 v6, s67
	ds_write_b32 v6, v2

.LBB0_543:
	s_cmp_ge_i32 s85, s80
	s_cbranch_scc1 .LBB0_545
	s_add_i32 s97, s84, 0x700
	v_add_u32_e32 v4, s97, v221
	v_lshl_add_u32 v4, v4, 11, v180
	v_add_u32_e32 v6, 0x4000000, v4
	global_load_dwordx4 v[130:133], v4, s[100:101]
	global_load_dwordx4 v[138:141], v6, s[100:101]
	v_add_u32_e32 v8, 0x10000, v4
	v_add_u32_e32 v5, 0x10000, v6
	global_load_dwordx4 v[142:145], v8, s[100:101]
	global_load_dwordx4 v[150:153], v5, s[100:101]

.LBB0_558:
	s_add_i32 s97, s84, 0x6c0
	v_add_u32_e32 v4, s97, v221
	v_lshl_add_u32 v4, v4, 11, v180
	v_add_u32_e32 v6, 0x4000000, v4
	global_load_dwordx4 v[134:137], v4, s[100:101]
	global_load_dwordx4 v[146:149], v6, s[100:101]
	v_add_u32_e32 v8, 0x10000, v4
	v_add_u32_e32 v5, 0x10000, v6
	global_load_dwordx4 v[154:157], v8, s[100:101]
	global_load_dwordx4 v[158:161], v5, s[100:101]
	s_branch .LBB0_530
